# grouped GEMM tile scheduler: expert lookup (count mpre[j]<=mt) as one per-lane ds_read + compare + popcount instead of 16 serialized LDS round trips per tile
# speedup vs baseline: 1.0190x; 1.0190x over previous
;     __device__ bool next(int i, Unit& u) const {
;         int mt, pn;
;         if ((G & 7) == 0 && (G >> 3) % nN == 0) { const int xcd = c & 7, j = c >> 3, per = (G >> 3) / nN; pn = j % nN; mt = (i * per + j / nN) * 8 + xcd; }
;         else { const int L = i * G + c; mt = L / nN; pn = L % nN; }
;         if (mt >= MT) return false;
;         u.pm = mt; u.pn = pn; int e = 0;
;         for (int j = 1; j < NEXP; ++j) e += (mpre[j] <= mt) ? 1 : 0;
;         u.e = __builtin_amdgcn_readfirstlane(e); return true;
;     }
.Lxf_skip_d1:
	s_cmp_lt_i32 s40, s15
	s_cselect_b64 s[20:21], -1, 0
	s_cmp_ge_i32 s40, s15
	v_readfirstlane_b32 s12, v168
	s_cbranch_scc1 .LBB0_28
	v_readlane_b32 s0, v254, 0
	v_lshlrev_b32_e32 v0, 2, v248
	s_nop 0
	v_add_u32_e32 v0, s0, v0
	ds_read_b32 v0, v0
	s_waitcnt lgkmcnt(0)
	v_cmp_ge_i32_e32 vcc, s40, v0
	s_nop 1
	s_and_b32 vcc_lo, vcc_lo, 0x7fffffff
	s_bcnt1_i32_b32 s56, vcc_lo

;     __device__ bool next(int i, Unit& u) const {
;         int mt, pn;
;         if ((G & 7) == 0 && (G >> 3) % nN == 0) { const int xcd = c & 7, j = c >> 3, per = (G >> 3) / nN; pn = j % nN; mt = (i * per + j / nN) * 8 + xcd; }
;         else { const int L = i * G + c; mt = L / nN; pn = L % nN; }
;         if (mt >= MT) return false;
;         u.pm = mt; u.pn = pn; int e = 0;
;         for (int j = 1; j < NEXP; ++j) e += (mpre[j] <= mt) ? 1 : 0;
;         u.e = __builtin_amdgcn_readfirstlane(e); return true;
;     }
.LBB0_39:
	s_cmp_lt_i32 s12, s15
	v_mov_b64_e32 v[202:203], 0x600
	s_cselect_b64 s[44:45], -1, 0
	s_cmp_ge_i32 s12, s15
	s_cbranch_scc1 .LBB0_41
	s_ashr_i32 s0, s17, 31
	s_lshr_b32 s0, s0, 30
	s_add_i32 s0, s17, s0
	s_and_b32 s0, s0, -4
	s_sub_i32 s38, s17, s0
	s_mov_b32 s50, s12
	v_readlane_b32 s0, v254, 0
	v_lshlrev_b32_e32 v0, 2, v248
	s_nop 0
	v_add_u32_e32 v0, s0, v0
	ds_read_b32 v0, v0
	s_waitcnt lgkmcnt(0)
	v_cmp_ge_i32_e32 vcc, s12, v0
	s_nop 1
	s_and_b32 vcc_lo, vcc_lo, 0x7fffffff
	s_bcnt1_i32_b32 s46, vcc_lo

;     __device__ bool next(int i, Unit& u) const {
;         int mt, pn;
;         if ((G & 7) == 0 && (G >> 3) % nN == 0) { const int xcd = c & 7, j = c >> 3, per = (G >> 3) / nN; pn = j % nN; mt = (i * per + j / nN) * 8 + xcd; }
;         else { const int L = i * G + c; mt = L / nN; pn = L % nN; }
;         if (mt >= MT) return false;
;         u.pm = mt; u.pn = pn; int e = 0;
;         for (int j = 1; j < NEXP; ++j) e += (mpre[j] <= mt) ? 1 : 0;
;         u.e = __builtin_amdgcn_readfirstlane(e); return true;
;     }
.LBB0_90:
	s_ashr_i32 s17, s16, 31
	s_lshr_b32 s17, s17, 29
	s_add_i32 s17, s16, s17
	s_and_b32 s17, s17, -8
	s_sub_i32 s40, s16, s17
	s_mov_b32 s94, s12
	v_readlane_b32 s16, v254, 0
	v_lshlrev_b32_e32 v0, 2, v248
	s_nop 0
	v_add_u32_e32 v0, s16, v0
	ds_read_b32 v0, v0
	s_waitcnt lgkmcnt(0)
	v_cmp_ge_i32_e32 vcc, s12, v0
	s_nop 1
	s_and_b32 vcc_lo, vcc_lo, 0x7fffffff
	s_bcnt1_i32_b32 s50, vcc_lo
